# attention tile loops: K-fragment LDS reads issued at the head of each tile body (behind the barrier), ahead of the scalar bookkeeping and prefetch address arithmetic
# baseline (speedup 1.0000x reference)
.LBB0_758:
	ds_read_b128 v[0:3], v159
	ds_read_b128 v[80:83], v160
	ds_read_b128 v[84:87], v161
	ds_read_b128 v[88:91], v162
	ds_read_b128 v[108:111], v163
	ds_read_b128 v[112:115], v164
	ds_read_b128 v[116:119], v165
	ds_read_b128 v[120:123], v166
	s_add_i32 s2, s68, -3
	s_cmp_lt_u32 s2, s63
	s_cselect_b64 s[2:3], -1, 0
	s_and_b64 s[12:13], s[2:3], exec
	s_cselect_b32 s18, 0, s63
	s_cselect_b32 s19, s64, s33
	s_add_i32 s71, s73, 2
	s_add_i32 s72, s68, -1
	s_cmp_lt_i32 s72, s62
	s_cselect_b64 s[60:61], -1, 0
	s_cmp_ge_i32 s72, s62
	s_cbranch_scc1 .LBB0_763
	s_cmp_ge_u32 s72, s63
	s_mov_b64 s[14:15], -1
	s_cbranch_scc0 .LBB0_761
	s_add_i32 s12, s70, s67
	s_addk_i32 s12, 0x80
	s_mov_b64 s[14:15], 0

.LBB0_764:
	v_add_u32_e32 v232, s12, v152
	v_ashrrev_i32_e32 v233, 31, v232
	v_lshlrev_b64 v[232:233], 7, v[232:233]
	s_ashr_i32 s13, s12, 31
	v_lshl_add_u64 v[232:233], v[146:147], 0, v[232:233]
	s_lshl_b64 s[12:13], s[12:13], 7
	global_load_dwordx4 v[40:43], v[232:233], off
	v_lshl_add_u64 v[232:233], v[148:149], 0, s[12:13]
	global_load_dwordx4 v[44:47], v[232:233], off
	v_cmp_gt_f32_e64 s[14:15], s31, v150
	v_cmp_gt_f32_e64 s[12:13], s31, v151
	s_nop 0
	v_cndmask_b32_e64 v15, v150, 0, s[14:15]
	v_cndmask_b32_e64 v12, v151, 0, s[12:13]
	v_xor_b32_e32 v124, 0x80000000, v15
	v_xor_b32_e32 v128, 0x80000000, v12
	v_mov_b32_e32 v125, v124
	v_mov_b32_e32 v126, v124
	v_mov_b32_e32 v127, v124
	v_mov_b32_e32 v129, v128
	v_mov_b32_e32 v130, v128
	v_mov_b32_e32 v131, v128
	s_waitcnt lgkmcnt(7)
	v_mfma_f32_16x16x32_bf16 v[92:95], v[0:3], v[16:19], v[124:127]
	s_or_b64 s[2:3], s[56:57], s[2:3]
	s_and_b64 vcc, exec, s[2:3]
	v_mfma_f32_16x16x32_bf16 v[0:3], v[0:3], v[24:27], v[128:131]
	s_waitcnt lgkmcnt(6)
	v_mfma_f32_16x16x32_bf16 v[104:107], v[80:83], v[20:23], v[92:95]
	v_mfma_f32_16x16x32_bf16 v[92:95], v[80:83], v[28:31], v[0:3]
	s_waitcnt lgkmcnt(5)
	v_mfma_f32_16x16x32_bf16 v[0:3], v[84:87], v[16:19], v[124:127]
	s_waitcnt lgkmcnt(4)
	v_mfma_f32_16x16x32_bf16 v[100:103], v[88:91], v[20:23], v[0:3]
	v_mfma_f32_16x16x32_bf16 v[0:3], v[84:87], v[24:27], v[128:131]
	v_mfma_f32_16x16x32_bf16 v[88:91], v[88:91], v[28:31], v[0:3]
	s_waitcnt lgkmcnt(3)
	v_mfma_f32_16x16x32_bf16 v[0:3], v[108:111], v[16:19], v[124:127]
	s_waitcnt lgkmcnt(2)
	v_mfma_f32_16x16x32_bf16 v[96:99], v[112:115], v[20:23], v[0:3]
	v_mfma_f32_16x16x32_bf16 v[0:3], v[108:111], v[24:27], v[128:131]
	v_mfma_f32_16x16x32_bf16 v[84:87], v[112:115], v[28:31], v[0:3]
	s_waitcnt lgkmcnt(1)
	v_mfma_f32_16x16x32_bf16 v[0:3], v[116:119], v[16:19], v[124:127]
	v_mfma_f32_16x16x32_bf16 v[80:83], v[116:119], v[24:27], v[128:131]
	s_waitcnt lgkmcnt(0)
	v_mfma_f32_16x16x32_bf16 v[0:3], v[120:123], v[20:23], v[0:3]
	v_mfma_f32_16x16x32_bf16 v[80:83], v[120:123], v[28:31], v[80:83]
	s_cbranch_vccnz .LBB0_770
	s_lshl_b32 s2, s18, 6
	s_sub_i32 s18, s19, s2
	s_mov_b64 s[2:3], -1
	s_and_b64 vcc, exec, s[58:59]
	s_cbranch_vccz .LBB0_767
	s_add_i32 s2, s67, s18
	s_ashr_i32 s19, s2, 6
	s_cmp_ge_i32 s19, s69
	s_cselect_b64 s[2:3], -1, 0
	s_sub_i32 s22, s19, s65
	s_mul_i32 s22, s22, 31
	v_sub_u32_e32 v14, s22, v155
	v_lshl_add_u32 v14, v14, 2, v157
	s_cmp_lt_i32 s19, s66
	ds_read_b32 v108, v14 offset:37792
	s_cselect_b64 s[20:21], -1, 0
	s_or_b64 s[2:3], s[20:21], s[2:3]
	v_readlane_b32 s20, v254, 17
	ds_read_b32 v109, v14 offset:37796
	v_readlane_b32 s21, v254, 18
	s_or_b64 vcc, s[2:3], s[20:21]
	v_readlane_b32 s20, v254, 19
	ds_read_b32 v110, v14 offset:37800
	s_waitcnt lgkmcnt(2)
	v_add_f32_e32 v108, v104, v108
	v_readlane_b32 s21, v254, 20
	v_cndmask_b32_e32 v108, v108, v227, vcc
	s_or_b64 vcc, s[2:3], s[20:21]
	v_readlane_b32 s20, v254, 15
	s_waitcnt lgkmcnt(1)
	v_add_f32_e32 v109, v105, v109
	v_readlane_b32 s21, v254, 16
	ds_read_b32 v111, v14 offset:37804
	v_cndmask_b32_e32 v109, v109, v227, vcc
	s_or_b64 vcc, s[2:3], s[20:21]
	v_readlane_b32 s20, v254, 58
	s_waitcnt lgkmcnt(1)
	v_add_f32_e32 v110, v106, v110
	v_readlane_b32 s21, v254, 59
	v_cndmask_b32_e32 v110, v110, v227, vcc
	s_or_b64 vcc, s[2:3], s[20:21]
	ds_read_b32 v112, v14 offset:37856
	v_readlane_b32 s20, v254, 60
	v_readlane_b32 s21, v254, 61
	v_readlane_b32 s24, v254, 62
	s_waitcnt lgkmcnt(1)
	v_add_f32_e32 v111, v107, v111
	s_or_b64 s[20:21], s[2:3], s[20:21]
	v_readlane_b32 s25, v254, 63
	v_cndmask_b32_e32 v111, v111, v227, vcc
	s_or_b64 vcc, s[20:21], s[24:25]
	ds_read_b32 v113, v14 offset:37860
	v_readlane_b32 s20, v255, 0
	v_readlane_b32 s21, v255, 1
	v_readlane_b32 s24, v255, 2
	s_waitcnt lgkmcnt(1)
	v_add_f32_e32 v112, v100, v112
	s_or_b64 s[20:21], s[2:3], s[20:21]
	v_readlane_b32 s25, v255, 3
	v_cndmask_b32_e32 v112, v112, v227, vcc
	s_or_b64 vcc, s[20:21], s[24:25]
	ds_read_b32 v114, v14 offset:37864
	v_readlane_b32 s20, v255, 4
	v_readlane_b32 s21, v255, 5
	v_readlane_b32 s24, v255, 6
	s_waitcnt lgkmcnt(1)
	v_add_f32_e32 v113, v101, v113
	s_or_b64 s[20:21], s[2:3], s[20:21]
	v_readlane_b32 s25, v255, 7
	v_cndmask_b32_e32 v113, v113, v227, vcc
	s_or_b64 vcc, s[20:21], s[24:25]
	ds_read_b32 v115, v14 offset:37868
	v_readlane_b32 s20, v255, 8
	v_readlane_b32 s21, v255, 9
	v_readlane_b32 s24, v255, 10
	s_waitcnt lgkmcnt(1)
	v_add_f32_e32 v114, v102, v114
	s_or_b64 s[20:21], s[2:3], s[20:21]
	v_readlane_b32 s25, v255, 11
	v_cndmask_b32_e32 v114, v114, v227, vcc
	s_or_b64 vcc, s[20:21], s[24:25]
	ds_read_b32 v116, v14 offset:37920
	v_readlane_b32 s20, v255, 12
	v_readlane_b32 s21, v255, 13
	v_readlane_b32 s24, v255, 14
	s_waitcnt lgkmcnt(1)
	v_add_f32_e32 v115, v103, v115
	s_or_b64 s[20:21], s[2:3], s[20:21]
	v_readlane_b32 s25, v255, 15
	v_cndmask_b32_e32 v115, v115, v227, vcc
	s_or_b64 vcc, s[20:21], s[24:25]
	ds_read_b32 v117, v14 offset:37924
	v_readlane_b32 s20, v255, 16
	v_readlane_b32 s21, v255, 17
	v_readlane_b32 s24, v255, 18
	s_waitcnt lgkmcnt(1)
	v_add_f32_e32 v116, v96, v116
	s_or_b64 s[20:21], s[2:3], s[20:21]
	v_readlane_b32 s25, v255, 19
	v_cndmask_b32_e32 v116, v116, v227, vcc
	s_or_b64 vcc, s[20:21], s[24:25]
	ds_read_b32 v118, v14 offset:37928
	v_readlane_b32 s20, v255, 20
	v_readlane_b32 s21, v255, 21
	v_readlane_b32 s24, v255, 22
	s_waitcnt lgkmcnt(1)
	v_add_f32_e32 v117, v97, v117
	s_or_b64 s[20:21], s[2:3], s[20:21]
	v_readlane_b32 s25, v255, 23
	ds_read_b32 v119, v14 offset:37932
	v_cndmask_b32_e32 v117, v117, v227, vcc
	s_or_b64 vcc, s[20:21], s[24:25]
	v_readlane_b32 s20, v255, 24
	v_readlane_b32 s21, v255, 25
	v_readlane_b32 s24, v255, 26
	ds_read_b32 v120, v14 offset:37984
	s_waitcnt lgkmcnt(2)
	v_add_f32_e32 v118, v98, v118
	s_or_b64 s[20:21], s[2:3], s[20:21]
	v_readlane_b32 s25, v255, 27
	v_cndmask_b32_e32 v118, v118, v227, vcc
	s_or_b64 vcc, s[20:21], s[24:25]
	v_readlane_b32 s20, v255, 28
	ds_read_b32 v121, v14 offset:37988
	s_waitcnt lgkmcnt(2)
	v_add_f32_e32 v119, v99, v119
	v_readlane_b32 s21, v255, 29
	v_cndmask_b32_e32 v119, v119, v227, vcc
	s_or_b64 vcc, s[2:3], s[20:21]
	v_readlane_b32 s20, v255, 30
	ds_read_b32 v122, v14 offset:37992
	s_waitcnt lgkmcnt(2)
	v_add_f32_e32 v120, v0, v120
	v_readlane_b32 s21, v255, 31
	ds_read_b32 v14, v14 offset:37996
	v_cndmask_b32_e32 v120, v120, v227, vcc
	s_or_b64 vcc, s[2:3], s[20:21]
	v_readlane_b32 s20, v255, 32
	s_waitcnt lgkmcnt(2)
	v_add_f32_e32 v121, v1, v121
	v_readlane_b32 s21, v255, 33
	v_cndmask_b32_e32 v121, v121, v227, vcc
	s_or_b64 vcc, s[2:3], s[20:21]
	v_readlane_b32 s20, v255, 34
	s_waitcnt lgkmcnt(1)
	v_add_f32_e32 v122, v2, v122
	v_readlane_b32 s21, v255, 35
	v_cndmask_b32_e32 v122, v122, v227, vcc
	s_waitcnt lgkmcnt(0)
	v_add_f32_e32 v14, v3, v14
	s_or_b64 vcc, s[2:3], s[20:21]
	v_cndmask_b32_e32 v123, v14, v227, vcc
	v_sub_u32_e32 v14, s22, v156
	v_lshl_add_u32 v14, v14, 2, v157
	ds_read_b32 v124, v14 offset:37792
	v_readlane_b32 s20, v255, 36
	ds_read_b32 v125, v14 offset:37796
	v_readlane_b32 s21, v255, 37
	s_or_b64 vcc, s[2:3], s[20:21]
	v_readlane_b32 s20, v255, 38
	ds_read_b32 v126, v14 offset:37800
	s_waitcnt lgkmcnt(2)
	v_add_f32_e32 v124, v92, v124
	v_readlane_b32 s21, v255, 39
	v_cndmask_b32_e32 v124, v124, v227, vcc
	s_or_b64 vcc, s[2:3], s[20:21]
	v_readlane_b32 s20, v255, 40
	s_waitcnt lgkmcnt(1)
	v_add_f32_e32 v125, v93, v125
	v_readlane_b32 s21, v255, 41
	ds_read_b32 v127, v14 offset:37804
	v_cndmask_b32_e32 v125, v125, v227, vcc
	s_or_b64 vcc, s[2:3], s[20:21]
	v_readlane_b32 s20, v255, 42
	ds_read_b32 v128, v14 offset:37856
	s_waitcnt lgkmcnt(2)
	v_add_f32_e32 v126, v94, v126
	v_readlane_b32 s21, v255, 43
	ds_read_b32 v129, v14 offset:37860
	v_cndmask_b32_e32 v126, v126, v227, vcc
	s_or_b64 vcc, s[2:3], s[20:21]
	v_readlane_b32 s20, v255, 44
	ds_read_b32 v130, v14 offset:37864
	v_readlane_b32 s21, v255, 45
	v_readlane_b32 s22, v255, 46
	ds_read_b32 v131, v14 offset:37868
	s_waitcnt lgkmcnt(4)
	v_add_f32_e32 v127, v95, v127
	s_or_b64 s[20:21], s[2:3], s[20:21]
	v_readlane_b32 s23, v255, 47
	ds_read_b32 v132, v14 offset:37920
	v_cndmask_b32_e32 v127, v127, v227, vcc
	s_waitcnt lgkmcnt(4)
	v_add_f32_e32 v128, v88, v128
	s_or_b64 vcc, s[20:21], s[22:23]
	s_or_b64 s[20:21], s[2:3], s[74:75]
	ds_read_b32 v133, v14 offset:37924
	v_cndmask_b32_e32 v128, v128, v227, vcc
	s_waitcnt lgkmcnt(4)
	v_add_f32_e32 v129, v89, v129
	s_or_b64 vcc, s[20:21], s[76:77]
	s_or_b64 s[20:21], s[2:3], s[78:79]
	ds_read_b32 v134, v14 offset:37928
	v_cndmask_b32_e32 v129, v129, v227, vcc
	s_waitcnt lgkmcnt(4)
	v_add_f32_e32 v130, v90, v130
	s_or_b64 vcc, s[20:21], s[80:81]
	s_or_b64 s[20:21], s[2:3], s[82:83]
	ds_read_b32 v135, v14 offset:37932
	v_cndmask_b32_e32 v130, v130, v227, vcc
	s_waitcnt lgkmcnt(4)
	v_add_f32_e32 v131, v91, v131
	s_or_b64 vcc, s[20:21], s[84:85]
	s_or_b64 s[20:21], s[2:3], s[86:87]
	ds_read_b32 v136, v14 offset:37984
	v_cndmask_b32_e32 v131, v131, v227, vcc
	s_waitcnt lgkmcnt(4)
	v_add_f32_e32 v132, v84, v132
	s_or_b64 vcc, s[20:21], s[88:89]
	s_or_b64 s[20:21], s[2:3], s[90:91]
	ds_read_b32 v137, v14 offset:37988
	v_cndmask_b32_e32 v132, v132, v227, vcc
	s_waitcnt lgkmcnt(4)
	v_add_f32_e32 v133, v85, v133
	s_or_b64 vcc, s[20:21], s[92:93]
	s_or_b64 s[20:21], s[2:3], s[94:95]
	ds_read_b32 v138, v14 offset:37992
	v_cndmask_b32_e32 v133, v133, v227, vcc
	s_waitcnt lgkmcnt(4)
	v_add_f32_e32 v134, v86, v134
	s_or_b64 vcc, s[20:21], s[96:97]
	s_or_b64 s[20:21], s[2:3], s[16:17]
	ds_read_b32 v14, v14 offset:37996
	v_cndmask_b32_e32 v134, v134, v227, vcc
	s_waitcnt lgkmcnt(4)
	v_add_f32_e32 v135, v87, v135
	s_or_b64 vcc, s[20:21], s[10:11]
	v_cndmask_b32_e32 v135, v135, v227, vcc
	s_waitcnt lgkmcnt(3)
	v_add_f32_e32 v136, v80, v136
	s_or_b64 vcc, s[2:3], s[8:9]
	v_cndmask_b32_e32 v136, v136, v227, vcc
	s_waitcnt lgkmcnt(2)
	v_add_f32_e32 v137, v81, v137
	s_or_b64 vcc, s[2:3], s[6:7]
	v_cndmask_b32_e32 v137, v137, v227, vcc
	s_waitcnt lgkmcnt(1)
	v_add_f32_e32 v138, v82, v138
	s_or_b64 vcc, s[2:3], s[4:5]
	v_cndmask_b32_e32 v138, v138, v227, vcc
	s_waitcnt lgkmcnt(0)
	v_add_f32_e32 v14, v83, v14
	s_or_b64 vcc, s[2:3], s[0:1]
	v_cndmask_b32_e32 v139, v14, v227, vcc
	s_mov_b64 s[2:3], 0

.LBB0_777:
	s_mov_b64 s[12:13], -1
	s_andn2_b64 vcc, exec, s[2:3]
	s_mov_b64 s[2:3], -1
	s_waitcnt lgkmcnt(0)
	s_barrier
	s_cbranch_vccnz .LBB0_799
	ds_read_b128 v[4:7], v159 offset:18432
	ds_read_b128 v[8:11], v160 offset:18432
	ds_read_b128 v[48:51], v161 offset:18432
	ds_read_b128 v[52:55], v162 offset:18432
	ds_read_b128 v[64:67], v163 offset:18432
	ds_read_b128 v[116:119], v164 offset:18432
	ds_read_b128 v[120:123], v165 offset:18432
	ds_read_b128 v[124:127], v166 offset:18432
	s_cmp_lt_u32 s14, s63
	s_cselect_b64 s[2:3], -1, 0
	s_and_b64 s[12:13], s[2:3], exec
	s_cselect_b32 s18, 0, s63
	s_cselect_b32 s19, s64, s33
	s_cmp_ge_i32 s68, s62
	s_cbranch_scc1 .LBB0_783
	s_cmp_ge_u32 s68, s63
	s_mov_b64 s[14:15], -1
	s_cbranch_scc0 .LBB0_781
	s_add_i32 s12, s70, s67
	s_addk_i32 s12, 0xc0
	s_mov_b64 s[14:15], 0

.LBB0_784:
	v_add_u32_e32 v232, s12, v152
	v_ashrrev_i32_e32 v233, 31, v232
	v_lshlrev_b64 v[232:233], 7, v[232:233]
	s_ashr_i32 s13, s12, 31
	v_lshl_add_u64 v[232:233], v[146:147], 0, v[232:233]
	s_lshl_b64 s[12:13], s[12:13], 7
	global_load_dwordx4 v[32:35], v[232:233], off
	v_lshl_add_u64 v[232:233], v[148:149], 0, s[12:13]
	global_load_dwordx4 v[36:39], v[232:233], off
	v_cmp_gt_f32_e64 s[14:15], s31, v14
	v_cmp_gt_f32_e64 s[12:13], s31, v15
	s_nop 0
	v_cndmask_b32_e64 v140, v14, 0, s[14:15]
	v_cndmask_b32_e64 v12, v15, 0, s[12:13]
	v_xor_b32_e32 v128, 0x80000000, v140
	v_xor_b32_e32 v132, 0x80000000, v12
	v_mov_b32_e32 v129, v128
	v_mov_b32_e32 v130, v128
	v_mov_b32_e32 v131, v128
	v_mov_b32_e32 v133, v132
	v_mov_b32_e32 v134, v132
	v_mov_b32_e32 v135, v132
	s_waitcnt lgkmcnt(7)
	v_mfma_f32_16x16x32_bf16 v[56:59], v[4:7], v[16:19], v[128:131]
	s_or_b64 s[2:3], s[56:57], s[2:3]
	s_and_b64 vcc, exec, s[2:3]
	v_mfma_f32_16x16x32_bf16 v[4:7], v[4:7], v[24:27], v[132:135]
	s_waitcnt lgkmcnt(6)
	v_mfma_f32_16x16x32_bf16 v[60:63], v[8:11], v[28:31], v[4:7]
	s_waitcnt lgkmcnt(5)
	v_mfma_f32_16x16x32_bf16 v[4:7], v[48:51], v[16:19], v[128:131]
	s_waitcnt lgkmcnt(4)
	v_mfma_f32_16x16x32_bf16 v[72:75], v[52:55], v[20:23], v[4:7]
	v_mfma_f32_16x16x32_bf16 v[4:7], v[48:51], v[24:27], v[132:135]
	v_mfma_f32_16x16x32_bf16 v[76:79], v[8:11], v[20:23], v[56:59]
	v_mfma_f32_16x16x32_bf16 v[56:59], v[52:55], v[28:31], v[4:7]
	s_waitcnt lgkmcnt(3)
	v_mfma_f32_16x16x32_bf16 v[4:7], v[64:67], v[16:19], v[128:131]
	s_waitcnt lgkmcnt(2)
	v_mfma_f32_16x16x32_bf16 v[68:71], v[116:119], v[20:23], v[4:7]
	v_mfma_f32_16x16x32_bf16 v[4:7], v[64:67], v[24:27], v[132:135]
	v_mfma_f32_16x16x32_bf16 v[52:55], v[116:119], v[28:31], v[4:7]
	s_waitcnt lgkmcnt(1)
	v_mfma_f32_16x16x32_bf16 v[4:7], v[120:123], v[16:19], v[128:131]
	s_waitcnt lgkmcnt(0)
	v_mfma_f32_16x16x32_bf16 v[64:67], v[124:127], v[20:23], v[4:7]
	v_mfma_f32_16x16x32_bf16 v[4:7], v[120:123], v[24:27], v[132:135]
	v_mfma_f32_16x16x32_bf16 v[48:51], v[124:127], v[28:31], v[4:7]
	s_cbranch_vccnz .LBB0_790
	s_lshl_b32 s2, s18, 6
	s_sub_i32 s18, s19, s2
	s_mov_b64 s[2:3], -1
	s_and_b64 vcc, exec, s[58:59]
	s_cbranch_vccz .LBB0_787
	s_add_i32 s2, s67, s18
	s_add_i32 s2, s2, 64
	s_ashr_i32 s19, s2, 6
	s_cmp_ge_i32 s19, s69
	s_cselect_b64 s[2:3], -1, 0
	s_sub_i32 s22, s19, s65
	s_mul_i32 s22, s22, 31
	v_sub_u32_e32 v4, s22, v155
	v_lshl_add_u32 v123, v4, 2, v157
	s_cmp_lt_i32 s19, s66
	ds_read_b32 v4, v123 offset:37792
	s_cselect_b64 s[20:21], -1, 0
	s_or_b64 s[2:3], s[20:21], s[2:3]
	v_readlane_b32 s20, v254, 17
	ds_read_b32 v5, v123 offset:37796
	v_readlane_b32 s21, v254, 18
	s_or_b64 vcc, s[2:3], s[20:21]
	v_readlane_b32 s20, v254, 19
	ds_read_b32 v6, v123 offset:37800
	s_waitcnt lgkmcnt(2)
	v_add_f32_e32 v4, v76, v4
	v_readlane_b32 s21, v254, 20
	v_cndmask_b32_e32 v4, v4, v227, vcc
	s_or_b64 vcc, s[2:3], s[20:21]
	v_readlane_b32 s20, v254, 15
	s_waitcnt lgkmcnt(1)
	v_add_f32_e32 v5, v77, v5
	v_readlane_b32 s21, v254, 16
	ds_read_b32 v7, v123 offset:37804
	v_cndmask_b32_e32 v5, v5, v227, vcc
	s_or_b64 vcc, s[2:3], s[20:21]
	v_readlane_b32 s20, v254, 58
	s_waitcnt lgkmcnt(1)
	v_add_f32_e32 v6, v78, v6
	v_readlane_b32 s21, v254, 59
	v_cndmask_b32_e32 v6, v6, v227, vcc
	s_or_b64 vcc, s[2:3], s[20:21]
	ds_read_b32 v8, v123 offset:37856
	v_readlane_b32 s20, v254, 60
	v_readlane_b32 s21, v254, 61
	v_readlane_b32 s24, v254, 62
	s_waitcnt lgkmcnt(1)
	v_add_f32_e32 v7, v79, v7
	s_or_b64 s[20:21], s[2:3], s[20:21]
	v_readlane_b32 s25, v254, 63
	v_cndmask_b32_e32 v7, v7, v227, vcc
	s_or_b64 vcc, s[20:21], s[24:25]
	ds_read_b32 v9, v123 offset:37860
	v_readlane_b32 s20, v255, 0
	v_readlane_b32 s21, v255, 1
	v_readlane_b32 s24, v255, 2
	s_waitcnt lgkmcnt(1)
	v_add_f32_e32 v8, v72, v8
	s_or_b64 s[20:21], s[2:3], s[20:21]
	v_readlane_b32 s25, v255, 3
	v_cndmask_b32_e32 v8, v8, v227, vcc
	s_or_b64 vcc, s[20:21], s[24:25]
	ds_read_b32 v10, v123 offset:37864
	v_readlane_b32 s20, v255, 4
	v_readlane_b32 s21, v255, 5
	v_readlane_b32 s24, v255, 6
	s_waitcnt lgkmcnt(1)
	v_add_f32_e32 v9, v73, v9
	s_or_b64 s[20:21], s[2:3], s[20:21]
	v_readlane_b32 s25, v255, 7
	v_cndmask_b32_e32 v9, v9, v227, vcc
	s_or_b64 vcc, s[20:21], s[24:25]
	ds_read_b32 v11, v123 offset:37868
	v_readlane_b32 s20, v255, 8
	v_readlane_b32 s21, v255, 9
	v_readlane_b32 s24, v255, 10
	s_waitcnt lgkmcnt(1)
	v_add_f32_e32 v10, v74, v10
	s_or_b64 s[20:21], s[2:3], s[20:21]
	v_readlane_b32 s25, v255, 11
	v_cndmask_b32_e32 v10, v10, v227, vcc
	s_or_b64 vcc, s[20:21], s[24:25]
	ds_read_b32 v116, v123 offset:37920
	v_readlane_b32 s20, v255, 12
	v_readlane_b32 s21, v255, 13
	v_readlane_b32 s24, v255, 14
	s_waitcnt lgkmcnt(1)
	v_add_f32_e32 v11, v75, v11
	s_or_b64 s[20:21], s[2:3], s[20:21]
	v_readlane_b32 s25, v255, 15
	v_cndmask_b32_e32 v11, v11, v227, vcc
	s_or_b64 vcc, s[20:21], s[24:25]
	ds_read_b32 v117, v123 offset:37924
	v_readlane_b32 s20, v255, 16
	v_readlane_b32 s21, v255, 17
	v_readlane_b32 s24, v255, 18
	s_waitcnt lgkmcnt(1)
	v_add_f32_e32 v116, v68, v116
	s_or_b64 s[20:21], s[2:3], s[20:21]
	v_readlane_b32 s25, v255, 19
	v_cndmask_b32_e32 v116, v116, v227, vcc
	s_or_b64 vcc, s[20:21], s[24:25]
	ds_read_b32 v118, v123 offset:37928
	v_readlane_b32 s20, v255, 20
	v_readlane_b32 s21, v255, 21
	v_readlane_b32 s24, v255, 22
	s_waitcnt lgkmcnt(1)
	v_add_f32_e32 v117, v69, v117
	s_or_b64 s[20:21], s[2:3], s[20:21]
	v_readlane_b32 s25, v255, 23
	ds_read_b32 v119, v123 offset:37932
	v_cndmask_b32_e32 v117, v117, v227, vcc
	s_or_b64 vcc, s[20:21], s[24:25]
	v_readlane_b32 s20, v255, 24
	v_readlane_b32 s21, v255, 25
	v_readlane_b32 s24, v255, 26
	ds_read_b32 v120, v123 offset:37984
	s_waitcnt lgkmcnt(2)
	v_add_f32_e32 v118, v70, v118
	s_or_b64 s[20:21], s[2:3], s[20:21]
	v_readlane_b32 s25, v255, 27
	v_cndmask_b32_e32 v118, v118, v227, vcc
	s_or_b64 vcc, s[20:21], s[24:25]
	v_readlane_b32 s20, v255, 28
	ds_read_b32 v121, v123 offset:37988
	s_waitcnt lgkmcnt(2)
	v_add_f32_e32 v119, v71, v119
	v_readlane_b32 s21, v255, 29
	v_cndmask_b32_e32 v119, v119, v227, vcc
	s_or_b64 vcc, s[2:3], s[20:21]
	v_readlane_b32 s20, v255, 30
	ds_read_b32 v122, v123 offset:37992
	s_waitcnt lgkmcnt(2)
	v_add_f32_e32 v120, v64, v120
	v_readlane_b32 s21, v255, 31
	v_cndmask_b32_e32 v120, v120, v227, vcc
	s_or_b64 vcc, s[2:3], s[20:21]
	v_readlane_b32 s20, v255, 32
	ds_read_b32 v123, v123 offset:37996
	v_sub_u32_e32 v124, s22, v156
	s_waitcnt lgkmcnt(2)
	v_add_f32_e32 v121, v65, v121
	v_readlane_b32 s21, v255, 33
	v_lshl_add_u32 v139, v124, 2, v157
	v_cndmask_b32_e32 v121, v121, v227, vcc
	s_or_b64 vcc, s[2:3], s[20:21]
	v_readlane_b32 s20, v255, 34
	ds_read_b32 v124, v139 offset:37792
	s_waitcnt lgkmcnt(2)
	v_add_f32_e32 v122, v66, v122
	v_readlane_b32 s21, v255, 35
	v_cndmask_b32_e32 v122, v122, v227, vcc
	s_or_b64 vcc, s[2:3], s[20:21]
	v_readlane_b32 s20, v255, 36
	ds_read_b32 v125, v139 offset:37796
	s_waitcnt lgkmcnt(2)
	v_add_f32_e32 v123, v67, v123
	v_readlane_b32 s21, v255, 37
	v_cndmask_b32_e32 v123, v123, v227, vcc
	s_or_b64 vcc, s[2:3], s[20:21]
	v_readlane_b32 s20, v255, 38
	ds_read_b32 v126, v139 offset:37800
	s_waitcnt lgkmcnt(2)
	v_add_f32_e32 v124, v60, v124
	v_readlane_b32 s21, v255, 39
	v_cndmask_b32_e32 v124, v124, v227, vcc
	s_or_b64 vcc, s[2:3], s[20:21]
	v_readlane_b32 s20, v255, 40
	s_waitcnt lgkmcnt(1)
	v_add_f32_e32 v125, v61, v125
	v_readlane_b32 s21, v255, 41
	ds_read_b32 v127, v139 offset:37804
	v_cndmask_b32_e32 v125, v125, v227, vcc
	s_or_b64 vcc, s[2:3], s[20:21]
	v_readlane_b32 s20, v255, 42
	ds_read_b32 v128, v139 offset:37856
	s_waitcnt lgkmcnt(2)
	v_add_f32_e32 v126, v62, v126
	v_readlane_b32 s21, v255, 43
	ds_read_b32 v129, v139 offset:37860
	v_cndmask_b32_e32 v126, v126, v227, vcc
	s_or_b64 vcc, s[2:3], s[20:21]
	v_readlane_b32 s20, v255, 44
	ds_read_b32 v130, v139 offset:37864
	v_readlane_b32 s21, v255, 45
	v_readlane_b32 s22, v255, 46
	ds_read_b32 v131, v139 offset:37868
	s_waitcnt lgkmcnt(4)
	v_add_f32_e32 v127, v63, v127
	s_or_b64 s[20:21], s[2:3], s[20:21]
	v_readlane_b32 s23, v255, 47
	ds_read_b32 v132, v139 offset:37920
	v_cndmask_b32_e32 v127, v127, v227, vcc
	s_waitcnt lgkmcnt(4)
	v_add_f32_e32 v128, v56, v128
	s_or_b64 vcc, s[20:21], s[22:23]
	s_or_b64 s[20:21], s[2:3], s[74:75]
	ds_read_b32 v133, v139 offset:37924
	v_cndmask_b32_e32 v128, v128, v227, vcc
	s_waitcnt lgkmcnt(4)
	v_add_f32_e32 v129, v57, v129
	s_or_b64 vcc, s[20:21], s[76:77]
	s_or_b64 s[20:21], s[2:3], s[78:79]
	ds_read_b32 v134, v139 offset:37928
	v_cndmask_b32_e32 v129, v129, v227, vcc
	s_waitcnt lgkmcnt(4)
	v_add_f32_e32 v130, v58, v130
	s_or_b64 vcc, s[20:21], s[80:81]
	s_or_b64 s[20:21], s[2:3], s[82:83]
	ds_read_b32 v135, v139 offset:37932
	v_cndmask_b32_e32 v130, v130, v227, vcc
	s_waitcnt lgkmcnt(4)
	v_add_f32_e32 v131, v59, v131
	s_or_b64 vcc, s[20:21], s[84:85]
	s_or_b64 s[20:21], s[2:3], s[86:87]
	ds_read_b32 v136, v139 offset:37984
	v_cndmask_b32_e32 v131, v131, v227, vcc
	s_waitcnt lgkmcnt(4)
	v_add_f32_e32 v132, v52, v132
	s_or_b64 vcc, s[20:21], s[88:89]
	s_or_b64 s[20:21], s[2:3], s[90:91]
	ds_read_b32 v137, v139 offset:37988
	v_cndmask_b32_e32 v132, v132, v227, vcc
	s_waitcnt lgkmcnt(4)
	v_add_f32_e32 v133, v53, v133
	s_or_b64 vcc, s[20:21], s[92:93]
	s_or_b64 s[20:21], s[2:3], s[94:95]
	ds_read_b32 v138, v139 offset:37992
	v_cndmask_b32_e32 v133, v133, v227, vcc
	s_waitcnt lgkmcnt(4)
	v_add_f32_e32 v134, v54, v134
	s_or_b64 vcc, s[20:21], s[96:97]
	s_or_b64 s[20:21], s[2:3], s[16:17]
	ds_read_b32 v139, v139 offset:37996
	v_cndmask_b32_e32 v134, v134, v227, vcc
	s_waitcnt lgkmcnt(4)
	v_add_f32_e32 v135, v55, v135
	s_or_b64 vcc, s[20:21], s[10:11]
	v_cndmask_b32_e32 v135, v135, v227, vcc
	s_waitcnt lgkmcnt(3)
	v_add_f32_e32 v136, v48, v136
	s_or_b64 vcc, s[2:3], s[8:9]
	v_cndmask_b32_e32 v136, v136, v227, vcc
	s_waitcnt lgkmcnt(2)
	v_add_f32_e32 v137, v49, v137
	s_or_b64 vcc, s[2:3], s[6:7]
	v_cndmask_b32_e32 v137, v137, v227, vcc
	s_waitcnt lgkmcnt(1)
	v_add_f32_e32 v138, v50, v138
	s_or_b64 vcc, s[2:3], s[4:5]
	v_cndmask_b32_e32 v138, v138, v227, vcc
	s_waitcnt lgkmcnt(0)
	v_add_f32_e32 v139, v51, v139
	s_or_b64 vcc, s[2:3], s[0:1]
	v_cndmask_b32_e32 v139, v139, v227, vcc
	s_mov_b64 s[2:3], 0

.LBB0_813:
	ds_read_b128 v[116:119], v198
	ds_read_b128 v[120:123], v199
	ds_read_b128 v[124:127], v200
	ds_read_b128 v[128:131], v201
	ds_read_b128 v[148:151], v202
	ds_read_b128 v[152:155], v203
	ds_read_b128 v[212:215], v204
	ds_read_b128 v[228:231], v205
	s_add_i32 s0, s11, -3
	s_cmp_lt_u32 s0, s63
	s_cselect_b32 s1, 0, s63
	s_cselect_b32 s0, s64, s33
	s_add_i32 s12, s14, 2
	s_add_i32 s13, s11, -1
	s_cmp_lt_i32 s13, s62
	s_cselect_b64 s[2:3], -1, 0
	s_cmp_ge_i32 s13, s62
	s_cbranch_scc1 .LBB0_818
	s_cmp_ge_u32 s13, s63
	s_mov_b64 s[4:5], -1
	s_cbranch_scc0 .LBB0_816
	s_sub_i32 s0, s10, 64
	s_mov_b64 s[4:5], 0

.LBB0_819:
	v_add_u32_e32 v14, s0, v196
	v_ashrrev_i32_e32 v15, 31, v14
	v_lshlrev_b64 v[14:15], 7, v[14:15]
	s_ashr_i32 s1, s0, 31
	v_lshl_add_u64 v[14:15], v[186:187], 0, v[14:15]
	s_lshl_b64 s[0:1], s[0:1], 7
	global_load_dwordx4 v[108:111], v[14:15], off
	v_lshl_add_u64 v[14:15], v[188:189], 0, s[0:1]
	global_load_dwordx4 v[112:115], v[14:15], off
	v_cmp_gt_f32_e32 vcc, s31, v207
	v_cmp_gt_f32_e64 s[4:5], s31, v208
	v_cmp_gt_f32_e64 s[6:7], s31, v209
	v_cmp_gt_f32_e64 s[0:1], s31, v210
	v_cndmask_b32_e64 v211, v207, 0, vcc
	v_cndmask_b32_e64 v15, v208, 0, s[4:5]
	v_cndmask_b32_e64 v14, v209, 0, s[6:7]
	v_cndmask_b32_e64 v12, v210, 0, s[0:1]
	v_xor_b32_e32 v168, 0x80000000, v211
	v_mov_b32_e32 v169, v168
	v_mov_b32_e32 v170, v168
	v_mov_b32_e32 v171, v168
	v_xor_b32_e32 v232, 0x80000000, v15
	v_xor_b32_e32 v236, 0x80000000, v14
	s_waitcnt lgkmcnt(3)
	v_mfma_f32_16x16x32_bf16 v[172:175], v[148:151], v[84:87], v[168:171]
	v_xor_b32_e32 v240, 0x80000000, v12
	v_mov_b32_e32 v233, v232
	v_mov_b32_e32 v234, v232
	s_waitcnt lgkmcnt(1)
	v_mfma_f32_16x16x32_bf16 v[176:179], v[212:215], v[84:87], v[168:171]
	v_mov_b32_e32 v235, v232
	v_mov_b32_e32 v237, v236
	v_mov_b32_e32 v238, v236
	v_mfma_f32_16x16x32_bf16 v[132:135], v[116:119], v[84:87], v[168:171]
	v_mov_b32_e32 v239, v236
	v_mov_b32_e32 v241, v240
	v_mov_b32_e32 v242, v240
	v_mfma_f32_16x16x32_bf16 v[136:139], v[124:127], v[84:87], v[168:171]
	v_mov_b32_e32 v243, v240
	v_mfma_f32_16x16x32_bf16 v[156:159], v[120:123], v[88:91], v[232:235]
	v_mfma_f32_16x16x32_bf16 v[140:143], v[116:119], v[92:95], v[236:239]
	v_mfma_f32_16x16x32_bf16 v[116:119], v[120:123], v[96:99], v[240:243]
	v_mfma_f32_16x16x32_bf16 v[160:163], v[128:131], v[88:91], v[232:235]
	v_mfma_f32_16x16x32_bf16 v[144:147], v[124:127], v[92:95], v[236:239]
	v_mfma_f32_16x16x32_bf16 v[120:123], v[128:131], v[96:99], v[240:243]
	v_mfma_f32_16x16x32_bf16 v[164:167], v[152:155], v[88:91], v[232:235]
	v_mfma_f32_16x16x32_bf16 v[148:151], v[148:151], v[92:95], v[236:239]
	v_mfma_f32_16x16x32_bf16 v[124:127], v[152:155], v[96:99], v[240:243]
	s_waitcnt lgkmcnt(0)
	v_mfma_f32_16x16x32_bf16 v[168:171], v[228:231], v[88:91], v[232:235]
	v_mfma_f32_16x16x32_bf16 v[152:155], v[212:215], v[92:95], v[236:239]
	v_max_i32_e32 v212, v172, v176
	v_max3_i32 v212, v132, v136, v212
	v_cmp_lt_i32_e64 s[8:9], s29, v212
	v_mfma_f32_16x16x32_bf16 v[128:131], v[228:231], v[96:99], v[240:243]
	s_or_b64 vcc, s[8:9], vcc
	s_cbranch_vccz .LBB0_821
	v_max_f32_e32 v212, v135, v135
	v_max_f32_e32 v213, v134, v134
	v_max_f32_e32 v212, v213, v212
	v_max_f32_e32 v213, v139, v139
	v_max_f32_e32 v214, v138, v138
	v_max_f32_e32 v213, v214, v213
	v_max_f32_e32 v214, v172, v172
	v_max_f32_e32 v215, v173, v173
	v_max_f32_e32 v214, v214, v215
	v_max_f32_e32 v215, v175, v175
	v_max_f32_e32 v220, v174, v174
	v_max_f32_e32 v215, v220, v215
	v_max_f32_e32 v220, v179, v179
	v_max_f32_e32 v221, v178, v178
	v_max_f32_e32 v220, v221, v220
	v_max3_f32 v220, v176, v177, v220
	v_max3_f32 v212, v132, v133, v212
	v_max3_f32 v213, v136, v137, v213
	v_max3_f32 v214, v214, v215, v220
	v_max3_f32 v212, v212, v213, v214
	v_and_b32_e32 v214, 64, v217
	v_xor_b32_e32 v213, 16, v217
	v_add_u32_e32 v214, 64, v214
	v_cmp_lt_i32_e32 vcc, v213, v214
	s_nop 1
	v_cndmask_b32_e32 v213, v217, v213, vcc
	v_lshlrev_b32_e32 v213, 2, v213
	ds_bpermute_b32 v213, v213, v212
	s_waitcnt lgkmcnt(0)
	v_max_f32_e32 v213, v213, v213
	v_max_f32_e32 v212, v212, v213
	v_xor_b32_e32 v213, 32, v217
	v_cmp_lt_i32_e32 vcc, v213, v214
	s_nop 1
	v_cndmask_b32_e32 v213, v217, v213, vcc
	v_lshlrev_b32_e32 v213, 2, v213
	ds_bpermute_b32 v213, v213, v212
	s_waitcnt lgkmcnt(0)
	v_max_f32_e32 v213, v213, v213
	v_max_f32_e32 v212, v212, v213
	v_add_f32_e32 v212, v211, v212
	v_max_f32_e32 v213, v207, v207
	v_max_f32_e32 v213, v213, v212
	v_sub_f32_e32 v207, v207, v213
	v_exp_f32_e32 v212, v207
	v_sub_f32_e32 v207, v213, v211
	v_sub_f32_e32 v135, v135, v207
	v_sub_f32_e32 v134, v134, v207
	v_pk_mul_f32 v[82:83], v[82:83], v[212:213] op_sel_hi:[1,0]
	v_pk_mul_f32 v[80:81], v[80:81], v[212:213] op_sel_hi:[1,0]
	v_sub_f32_e32 v133, v133, v207
	v_sub_f32_e32 v132, v132, v207
	v_sub_f32_e32 v139, v139, v207
	v_sub_f32_e32 v138, v138, v207
	v_sub_f32_e32 v137, v137, v207
	v_sub_f32_e32 v136, v136, v207
	v_sub_f32_e32 v175, v175, v207
	v_sub_f32_e32 v174, v174, v207
	v_sub_f32_e32 v173, v173, v207
	v_sub_f32_e32 v172, v172, v207
	v_sub_f32_e32 v179, v179, v207
	v_sub_f32_e32 v178, v178, v207
	v_sub_f32_e32 v177, v177, v207
	v_sub_f32_e32 v176, v176, v207
	v_pk_mul_f32 v[74:75], v[74:75], v[212:213] op_sel_hi:[1,0]
	v_pk_mul_f32 v[72:73], v[72:73], v[212:213] op_sel_hi:[1,0]
	v_pk_mul_f32 v[66:67], v[66:67], v[212:213] op_sel_hi:[1,0]
	v_pk_mul_f32 v[64:65], v[64:65], v[212:213] op_sel_hi:[1,0]
	v_pk_mul_f32 v[58:59], v[58:59], v[212:213] op_sel_hi:[1,0]
	v_pk_mul_f32 v[56:57], v[56:57], v[212:213] op_sel_hi:[1,0]
	v_pk_mul_f32 v[54:55], v[54:55], v[212:213] op_sel_hi:[1,0]
	v_pk_mul_f32 v[52:53], v[52:53], v[212:213] op_sel_hi:[1,0]
	v_mov_b32_e32 v207, v213

.LBB0_829:
	s_andn2_b64 vcc, exec, s[0:1]
	s_mov_b64 s[0:1], -1
	s_waitcnt lgkmcnt(0)
	s_barrier
	s_cbranch_vccnz .LBB0_833
	ds_read_b128 v[116:119], v198 offset:18432
	ds_read_b128 v[120:123], v199 offset:18432
	ds_read_b128 v[124:127], v200 offset:18432
	ds_read_b128 v[136:139], v201 offset:18432
	ds_read_b128 v[144:147], v202 offset:18432
	ds_read_b128 v[160:163], v203 offset:18432
	ds_read_b128 v[212:215], v204 offset:18432
	ds_read_b128 v[228:231], v205 offset:18432
	s_cmp_lt_u32 s4, s63
	s_cselect_b32 s1, 0, s63
	s_cselect_b32 s0, s64, s33
	s_cmp_ge_i32 s11, s62
	s_cbranch_scc1 .LBB0_834
	s_cmp_ge_u32 s11, s63
	s_mov_b32 s0, s10
	s_cbranch_scc1 .LBB0_835
	s_lshl_b32 s0, s14, 6
	s_add_i32 s0, s0, s64
	s_addk_i32 s0, 0xc0
	s_branch .LBB0_835

.LBB0_835:
	v_add_u32_e32 v14, s0, v196
	v_ashrrev_i32_e32 v15, 31, v14
	v_lshlrev_b64 v[14:15], 7, v[14:15]
	s_ashr_i32 s1, s0, 31
	v_lshl_add_u64 v[14:15], v[186:187], 0, v[14:15]
	s_lshl_b64 s[0:1], s[0:1], 7
	global_load_dwordx4 v[100:103], v[14:15], off
	v_lshl_add_u64 v[14:15], v[188:189], 0, s[0:1]
	global_load_dwordx4 v[104:107], v[14:15], off
	v_cmp_gt_f32_e32 vcc, s31, v207
	v_cmp_gt_f32_e64 s[4:5], s31, v208
	v_cmp_gt_f32_e64 s[6:7], s31, v209
	v_cmp_gt_f32_e64 s[0:1], s31, v210
	v_cndmask_b32_e64 v211, v207, 0, vcc
	v_cndmask_b32_e64 v15, v208, 0, s[4:5]
	v_cndmask_b32_e64 v14, v209, 0, s[6:7]
	v_cndmask_b32_e64 v12, v210, 0, s[0:1]
	v_xor_b32_e32 v232, 0x80000000, v211
	v_xor_b32_e32 v236, 0x80000000, v15
	v_xor_b32_e32 v240, 0x80000000, v14
	v_xor_b32_e32 v244, 0x80000000, v12
	v_mov_b32_e32 v233, v232
	v_mov_b32_e32 v234, v232
	v_mov_b32_e32 v235, v232
	v_mov_b32_e32 v237, v236
	v_mov_b32_e32 v238, v236
	v_mov_b32_e32 v239, v236
	v_mov_b32_e32 v241, v240
	v_mov_b32_e32 v242, v240
	v_mov_b32_e32 v243, v240
	v_mov_b32_e32 v245, v244
	v_mov_b32_e32 v246, v244
	v_mov_b32_e32 v247, v244
	s_waitcnt lgkmcnt(5)
	v_mfma_f32_16x16x32_bf16 v[176:179], v[124:127], v[84:87], v[232:235]
	s_waitcnt lgkmcnt(4)
	v_mfma_f32_16x16x32_bf16 v[168:171], v[136:139], v[88:91], v[236:239]
	v_mfma_f32_16x16x32_bf16 v[152:155], v[124:127], v[92:95], v[240:243]
	v_mfma_f32_16x16x32_bf16 v[124:127], v[136:139], v[96:99], v[244:247]
	s_waitcnt lgkmcnt(3)
	v_mfma_f32_16x16x32_bf16 v[172:175], v[144:147], v[84:87], v[232:235]
	s_waitcnt lgkmcnt(1)
	v_mfma_f32_16x16x32_bf16 v[136:139], v[212:215], v[84:87], v[232:235]
	v_mfma_f32_16x16x32_bf16 v[132:135], v[116:119], v[84:87], v[232:235]
	v_mfma_f32_16x16x32_bf16 v[156:159], v[120:123], v[88:91], v[236:239]
	v_mfma_f32_16x16x32_bf16 v[140:143], v[116:119], v[92:95], v[240:243]
	v_mfma_f32_16x16x32_bf16 v[128:131], v[120:123], v[96:99], v[244:247]
	v_mfma_f32_16x16x32_bf16 v[164:167], v[160:163], v[88:91], v[236:239]
	v_mfma_f32_16x16x32_bf16 v[148:151], v[144:147], v[92:95], v[240:243]
	v_mfma_f32_16x16x32_bf16 v[120:123], v[160:163], v[96:99], v[244:247]
	s_waitcnt lgkmcnt(0)
	v_mfma_f32_16x16x32_bf16 v[160:163], v[228:231], v[88:91], v[236:239]
	v_mfma_f32_16x16x32_bf16 v[144:147], v[212:215], v[92:95], v[240:243]
	v_max_i32_e32 v212, v172, v136
	v_max3_i32 v212, v132, v176, v212
	v_cmp_lt_i32_e64 s[8:9], s29, v212
	v_mfma_f32_16x16x32_bf16 v[116:119], v[228:231], v[96:99], v[244:247]
	s_or_b64 vcc, s[8:9], vcc
	s_cbranch_vccz .LBB0_837
	v_max_f32_e32 v212, v135, v135
	v_max_f32_e32 v213, v134, v134
	v_max_f32_e32 v212, v213, v212
	v_max_f32_e32 v213, v179, v179
	v_max_f32_e32 v214, v178, v178
	v_max_f32_e32 v213, v214, v213
	v_max_f32_e32 v214, v172, v172
	v_max_f32_e32 v215, v173, v173
	v_max_f32_e32 v214, v214, v215
	v_max_f32_e32 v215, v175, v175
	v_max_f32_e32 v220, v174, v174
	v_max_f32_e32 v215, v220, v215
	v_max_f32_e32 v220, v139, v139
	v_max_f32_e32 v221, v138, v138
	v_max_f32_e32 v220, v221, v220
	v_max3_f32 v220, v136, v137, v220
	v_max3_f32 v212, v132, v133, v212
	v_max3_f32 v213, v176, v177, v213
	v_max3_f32 v214, v214, v215, v220
	v_max3_f32 v212, v212, v213, v214
	v_and_b32_e32 v214, 64, v217
	v_xor_b32_e32 v213, 16, v217
	v_add_u32_e32 v214, 64, v214
	v_cmp_lt_i32_e32 vcc, v213, v214
	s_nop 1
	v_cndmask_b32_e32 v213, v217, v213, vcc
	v_lshlrev_b32_e32 v213, 2, v213
	ds_bpermute_b32 v213, v213, v212
	s_waitcnt lgkmcnt(0)
	v_max_f32_e32 v213, v213, v213
	v_max_f32_e32 v212, v212, v213
	v_xor_b32_e32 v213, 32, v217
	v_cmp_lt_i32_e32 vcc, v213, v214
	s_nop 1
	v_cndmask_b32_e32 v213, v217, v213, vcc
	v_lshlrev_b32_e32 v213, 2, v213
	ds_bpermute_b32 v213, v213, v212
	s_waitcnt lgkmcnt(0)
	v_max_f32_e32 v213, v213, v213
	v_max_f32_e32 v212, v212, v213
	v_add_f32_e32 v212, v211, v212
	v_max_f32_e32 v213, v207, v207
	v_max_f32_e32 v213, v213, v212
	v_sub_f32_e32 v207, v207, v213
	v_exp_f32_e32 v212, v207
	v_sub_f32_e32 v207, v213, v211
	v_sub_f32_e32 v135, v135, v207
	v_sub_f32_e32 v134, v134, v207
	v_pk_mul_f32 v[82:83], v[82:83], v[212:213] op_sel_hi:[1,0]
	v_pk_mul_f32 v[80:81], v[80:81], v[212:213] op_sel_hi:[1,0]
	v_sub_f32_e32 v133, v133, v207
	v_sub_f32_e32 v132, v132, v207
	v_sub_f32_e32 v179, v179, v207
	v_sub_f32_e32 v178, v178, v207
	v_sub_f32_e32 v177, v177, v207
	v_sub_f32_e32 v176, v176, v207
	v_sub_f32_e32 v175, v175, v207
	v_sub_f32_e32 v174, v174, v207
	v_sub_f32_e32 v173, v173, v207
	v_sub_f32_e32 v172, v172, v207
	v_sub_f32_e32 v139, v139, v207
	v_sub_f32_e32 v138, v138, v207
	v_sub_f32_e32 v137, v137, v207
	v_sub_f32_e32 v136, v136, v207
	v_pk_mul_f32 v[74:75], v[74:75], v[212:213] op_sel_hi:[1,0]
	v_pk_mul_f32 v[72:73], v[72:73], v[212:213] op_sel_hi:[1,0]
	v_pk_mul_f32 v[66:67], v[66:67], v[212:213] op_sel_hi:[1,0]
	v_pk_mul_f32 v[64:65], v[64:65], v[212:213] op_sel_hi:[1,0]
	v_pk_mul_f32 v[58:59], v[58:59], v[212:213] op_sel_hi:[1,0]
	v_pk_mul_f32 v[56:57], v[56:57], v[212:213] op_sel_hi:[1,0]
	v_pk_mul_f32 v[54:55], v[54:55], v[212:213] op_sel_hi:[1,0]
	v_pk_mul_f32 v[52:53], v[52:53], v[212:213] op_sel_hi:[1,0]
	v_mov_b32_e32 v207, v213
